# P1 in-projection K-loop restructured: 64 MFMAs per barrier pair (2 barriers per K-tile instead of 4), whole-K-tile fragments in registers, leading half stages B, trailing half stages A
# speedup vs baseline: 1.0059x; 1.0002x over previous
; #define LAS __attribute__((address_space(3)))
; template <class Epi, class Sched, bool ALIGN_EPI = false, bool SP2 = false>
; __device__ __forceinline__ void gemm_phase(PG8_LAS unsigned char* lds, const Gemm g, const Sched& S, const Epi& E) {
;     ...
;     const int tid = tid_, wid = __builtin_amdgcn_readfirstlane(tid >> 6), lane = tid & 63, wr = wid >> 2, wc = wid & 3, fr = lane & 15, fq = lane >> 4;
; __global__ void __launch_bounds__(NWAVES * 64, 2) fwd_kernel(Args args) {
;     extern __shared__ __attribute__((aligned(16))) unsigned char lds[];
;     Frame F;
;     F.lds = (LAS unsigned char*)lds;
;     F.MISC = (volatile LAS unsigned*)(F.lds + MISC_OFF);
;     F.tid = threadIdx.x; F.lane = F.tid & 63; F.wave = __builtin_amdgcn_readfirstlane(F.tid >> 6);
;     F.G = gridDim.x; { const int bx = blockIdx.x; F.vcu = (F.G % 8 == 0) ? (bx % 8) * (F.G / 8) + bx / 8 : bx; }
_Z10fwd_kernel4Args:
	s_load_dword s97, s[0:1], 0xb8
	s_mov_b32 s96, s2
	s_add_u32 s2, s0, 0xb8
	s_addc_u32 s3, s1, 0
	s_mov_b32 s62, s96
	v_writelane_b32 v254, s2, 0
	v_readfirstlane_b32 s6, v0
	s_nop 0
	v_writelane_b32 v254, s3, 1
	s_lshr_b32 s101, s6, 8
	s_waitcnt lgkmcnt(0)
	s_and_b32 s2, s97, 7
	s_cmp_lg_u32 s2, 0
	v_writelane_b32 v254, s62, 2
	s_cbranch_scc1 .LBB0_2
	s_ashr_i32 s3, s96, 31
	s_lshr_b32 s3, s3, 29
	s_add_i32 s3, s96, s3
	s_and_b32 s4, s3, -8
	s_ashr_i32 s2, s97, 3
	s_sub_i32 s4, s96, s4
	s_mul_i32 s2, s2, s4
	s_ashr_i32 s3, s3, 3
	s_add_i32 s2, s2, s3
	v_writelane_b32 v254, s2, 2

;     __host__ __device__ bool next(int i, Unit& u) const { if (!StaticOrder::next(i >> 1, u)) return false; u.kh = i & 1; return true; }
; template <class Epi, class Sched, bool ALIGN_EPI = false, bool SP2 = false>
; __device__ __forceinline__ void gemm_phase(PG8_LAS unsigned char* lds, const Gemm g, const Sched& S, const Epi& E) {
;     ...
;     const int tid = tid_, wid = __builtin_amdgcn_readfirstlane(tid >> 6), lane = tid & 63, wr = wid >> 2, wc = wid & 3, fr = lane & 15, fq = lane >> 4;
;     const int K = g.K, nt = K / BK;
;     unsigned voffA[2], voffB[2];
; #pragma unroll
;     for (int i = 0; i < 2; ++i) { int R, C; stage_rc(tid * 16 + i * 8192, R, C); const int Rb = Epi::PERM ? ((R & ~31) + perm32(R & 31)) : R;
;         voffA[i] = (unsigned)(R * g.lda + C) * 2u; voffB[i] = (unsigned)(Rb * BK + C) * 2u; }
;     const size_t kstep = (size_t)(BK * 2);
;     const size_t hstepA = (size_t)HALF * g.lda * 2, hstepB = (size_t)HALF * BK * 2;
;     const size_t tstepA = 2 * hstepA, tstepB = (size_t)(g.ldb / BK) * (BM * BK * 2);
;     const size_t segstep = (size_t)K * 2, segstepB = (size_t)nt * (BM * BK * 2);
;     const size_t kstepB = (size_t)(BM * BK * 2);
;     const unsigned ldsw = (unsigned)wid * 1024u;
;     const int aoff = lds_byte(wr * 64 + fr, fq * 8), boff = lds_byte(wc * 32 + fr, fq * 8);
;     ...
;     Unit cur, nxt; int ui = 0;
;     if (!S.next(0, cur)) return;
;     f32x4 acc[2][2][4][2];
; #pragma unroll
;     for (int a = 0; a < 2; ++a)
; #pragma unroll
;         for (int b = 0; b < 2; ++b)
; #pragma unroll
;             for (int m = 0; m < 4; ++m)
; #pragma unroll
;                 for (int n = 0; n < 2; ++n) acc[a][b][m][n] = (f32x4){0.f, 0.f, 0.f, 0.f};
;     bf16x8 At[4][2], B0[2][2], B1[2][2];
;     const char* cA = (const char*)g.A + (size_t)cur.pm * tstepA + (size_t)cur.kh * segstep; const char* cB = (const char*)g.Bt + (size_t)cur.pn * tstepB + (size_t)cur.kh * segstepB;
;     S.a_ready(cur);
;     if constexpr (SP2) {
;         PG8_STAGE(PG8_SB(0, 0), cB, voffB); PG8_STAGE(PG8_SB(0, 1), cB + hstepB, voffB); PG8_STAGE(PG8_SA(0, 0), cA, voffA); PG8_STAGE(PG8_SA(0, 1), cA + hstepA, voffA);
;         if (wr == 1) PG8_BAR;
;         PG8_WAIT_V(2); PG8_BAR;
;         PG8_STAGE(PG8_SB(1, 0), cB + kstepB, voffB); PG8_STAGE(PG8_SA(1, 0), cA + kstep, voffA); PG8_STAGE(PG8_SB(1, 1), cB + hstepB + kstepB, voffB);
;         PG8_WAIT_V(6); PG8_BAR;
.LBB0_111:
	s_lshl_b32 s14, s14, 5
	s_and_b32 s20, s14, 0x60
	s_lshl_b32 s46, s5, 6
	s_lshl_b32 s5, s5, 13
	s_lshl_b32 s17, s20, 7
	s_add_u32 s14, s34, 0x8000
	s_addc_u32 s15, s35, 0
	s_add_i32 m0, s42, 0x18000
	v_lshl_add_u64 v[14:15], s[14:15], 0, v[132:133]
	s_waitcnt vmcnt(0)
	s_barrier
	global_load_lds_dwordx4 v[14:15], off
	v_lshl_add_u64 v[14:15], s[14:15], 0, v[136:137]
	s_add_i32 m0, s42, 0x1a000
	s_mov_b64 s[14:15], 0x80
	s_add_i32 s47, s42, 0x8000
	s_add_i32 s48, s42, 0xa000
	global_load_lds_dwordx4 v[14:15], off
	v_lshl_add_u64 v[2:3], v[2:3], 0, s[14:15]
	s_mov_b32 m0, s47
	s_add_u32 s18, s34, 0xc000
	global_load_lds_dwordx4 v[2:3], off
	v_lshl_add_u64 v[2:3], v[4:5], 0, s[14:15]
	s_mov_b32 m0, s48
	s_addc_u32 s19, s35, 0
	global_load_lds_dwordx4 v[2:3], off
	s_add_i32 m0, s42, 0x1c000
	v_lshl_add_u64 v[2:3], s[18:19], 0, v[132:133]
	global_load_lds_dwordx4 v[2:3], off
	v_lshl_add_u64 v[2:3], s[18:19], 0, v[136:137]
	s_add_i32 m0, s42, 0x1e000
	v_and_b32_e32 v1, 15, v6
	global_load_lds_dwordx4 v[2:3], off
	v_lshrrev_b32_e32 v2, 1, v6
	v_and_b32_e32 v2, 24, v2
	v_lshlrev_b32_e32 v138, 1, v2
	v_lshlrev_b32_e32 v4, 2, v6
	v_lshl_or_b32 v3, v1, 6, v138
	v_and_b32_e32 v4, 32, v4
	s_cmpk_lt_u32 s16, 0x100
	s_sext_i32_i16 s53, s4
	v_bitop3_b32 v154, v3, s17, v4 bitop3:0xde
	s_cselect_b64 s[16:17], -1, 0
	s_ashr_i32 s49, s97, 31
	s_lshl_b32 s4, s20, 1
	s_add_u32 s4, s10, s4
	v_bitop3_b32 v5, v3, s5, v4 bitop3:0xde
	s_addc_u32 s5, s11, 0
	v_or_b32_e32 v155, s20, v2
	v_lshl_add_u64 v[2:3], s[4:5], 0, v[138:139]
	s_mov_b64 s[4:5], 0x59700000
	v_lshl_add_u64 v[140:141], v[2:3], 0, s[4:5]
	v_lshlrev_b32_e32 v2, 16, v7
	v_and_b32_e32 v2, 0xfffe0000, v2
	v_lshl_add_u32 v2, v8, 13, v2
	v_and_b32_e32 v3, 1, v7
	v_lshl_or_b32 v2, v3, 6, v2
	v_lshl_add_u32 v142, v9, 1, v2
	v_lshlrev_b32_e32 v2, 16, v10
	v_and_b32_e32 v2, 0xfffe0000, v2
	s_waitcnt vmcnt(6)
	v_lshl_add_u32 v2, v11, 13, v2
	v_and_b32_e32 v3, 1, v10
	v_lshl_or_b32 v2, v3, 6, v2
	s_add_i32 s50, 0, 0x10000
	s_add_i32 s51, 0, 0x14000
	s_mov_b32 s33, 0xa000
	v_or_b32_e32 v156, 0xffffd000, v155
	v_mov_b32_e32 v143, v139
	v_lshl_add_u32 v144, v12, 1, v2
	v_mov_b32_e32 v145, v139
	s_mov_b64 s[18:19], 0x2000
	v_mov_b64_e32 v[146:147], 0x2000
	v_mov_b64_e32 v[148:149], 0x1fff
	v_add_u32_e32 v157, s50, v154
	v_add_u32_e32 v158, s51, v154
	v_add_u32_e32 v159, 0, v5
	s_mov_b64 s[20:21], 0x1000
	s_mov_b64 s[22:23], 0x3000
	s_mov_b32 s52, 0
	s_and_b32 s98, s42, 0xfff
	s_lshl_b32 s99, s101, 18
	s_lshl_b32 s100, s101, 12
	v_subrev_u32_e32 v130, s99, v130
	v_subrev_u32_e32 v134, s99, v134
	v_subrev_u32_e32 v132, s100, v132
	v_subrev_u32_e32 v136, s100, v136
	v_add_u32_e32 v131, 0x40000, v130
	v_add_u32_e32 v135, 0x40000, v134
	v_add_u32_e32 v133, 0x1000, v132
	v_add_u32_e32 v137, 0x1000, v136
	s_barrier
	s_branch .LBB0_114

;     __host__ __device__ bool next(int i, Unit& u) const { if (i > 0 || c >= 256) return false; u.pm = c >> 2; u.pn = 0; u.kh = c & 3; return true; }
;     __host__ __device__ bool next(int i, Unit& u) const { if (!StaticOrder::next(i >> 1, u)) return false; u.kh = i & 1; return true; }
; #define PG8_STAGE(bufoff, gbase, voff) do { _Pragma("unroll") for (int _i = 0; _i < 2; ++_i) \
;         __builtin_amdgcn_global_load_lds((const unsigned*)((const char*)(gbase) + (voff)[_i]), (PG8_LAS unsigned*)(lds + (bufoff) + ldsw + _i * 8192), 16, 0, 0); } while (0)
; #define PG8_WAIT_V(n) asm volatile("s_waitcnt vmcnt(" #n ")" ::: "memory")
; #define PG8_BAR __builtin_amdgcn_s_barrier()
; template <class Epi, class Sched, bool ALIGN_EPI = false, bool SP2 = false>
; __device__ __forceinline__ void gemm_phase(PG8_LAS unsigned char* lds, const Gemm g, const Sched& S, const Epi& E) {
;     ...
;         const bool has_next = S.next(ui + 1, nxt);
;         const char* nA = has_next ? (const char*)g.A + (size_t)nxt.pm * tstepA + (size_t)nxt.kh * segstep : cA; const char* nB = has_next ? (const char*)g.Bt + (size_t)nxt.pn * tstepB + (size_t)nxt.kh * segstepB : cB;
;         for (int t = 0; t < nt; t += 2) {
;             const bool last = (t == nt - 2);
;             const char* a1 = cA + (size_t)(t + 1) * kstep;
;             const char* a2 = last ? nA : cA + (size_t)(t + 2) * kstep; const char* b2 = last ? nB : cB + (size_t)(t + 2) * kstepB;
;             const char* a3 = a2 + kstep; const char* b3 = b2 + kstepB;
;             if (last && has_next) S.a_ready(nxt);
;             if constexpr (SP2) {
;             PG8_LDB(B0, 0, 0); PG8_LDB(B1, 0, 1); PG8_SCHED; PG8_LDA(At, 0, 0); PG8_STAGE(PG8_SA(1, 1), a1 + hstepA, voffA);
;             PG8_WAIT_V(8); PG8_WAIT_L(0); PG8_BAR; PG8_MMA(0, 0, At, B0); PG8_MMA(0, 1, At, B1); PG8_BAR; PG8_SCHED;
;             PG8_LDA(At, 0, 1); PG8_STAGE(PG8_SB(0, 0), b2, voffB); PG8_STAGE(PG8_SB(0, 1), b2 + hstepB, voffB); PG8_STAGE(PG8_SA(0, 0), a2, voffA);
;     ...
;         if (!(Epi::TWOSTEP && cur.kh == 0))
; #pragma unroll
;         for (int a = 0; a < 2; ++a)
; #pragma unroll
;             for (int b = 0; b < 2; ++b)
; #pragma unroll
;                 for (int m = 0; m < 4; ++m)
; #pragma unroll
;                     for (int n = 0; n < 2; ++n) acc[a][b][m][n] = (f32x4){0.f, 0.f, 0.f, 0.f};
;         cur = nxt; cA = nA; cB = nB; ++ui;
.LBB0_120:
	s_ashr_i32 s27, s26, 31
	s_lshl_b64 s[28:29], s[26:27], 21
	v_readlane_b32 s30, v254, 23
	v_readlane_b32 s31, v254, 24
	s_add_u32 s28, s30, s28
	s_addc_u32 s29, s31, s29
	s_and_b64 s[30:31], s[4:5], exec
	s_cselect_b32 s27, s29, s37
	s_cselect_b32 s54, s28, s36
	s_ashr_i32 s25, s24, 31
	s_lshl_b64 s[30:31], s[24:25], 21
	s_add_u32 s30, s3, s30
	s_addc_u32 s31, s40, s31
	s_and_b64 s[38:39], s[4:5], exec
	s_cselect_b32 s25, s31, s35
	s_cselect_b32 s55, s30, s34
	s_add_u32 s56, s34, 0x10000
	s_addc_u32 s57, s35, 0
	s_add_u32 s34, s36, 0x100080
	v_mov_b32_e32 v2, 0
	s_addc_u32 s35, s37, 0
	s_mov_b32 s58, -2
	v_mov_b32_e32 v3, v2
	v_mov_b32_e32 v4, v2
	v_mov_b32_e32 v5, v2
	v_mov_b32_e32 v6, v2
	v_mov_b32_e32 v7, v2
	v_mov_b32_e32 v8, v2
	v_mov_b32_e32 v9, v2
	v_mov_b32_e32 v10, v2
	v_mov_b32_e32 v11, v2
	v_mov_b32_e32 v12, v2
	v_mov_b32_e32 v13, v2
	v_mov_b32_e32 v14, v2
	v_mov_b32_e32 v15, v2
	v_mov_b32_e32 v16, v2
	v_mov_b32_e32 v17, v2
	v_mov_b32_e32 v26, v2
	v_mov_b32_e32 v27, v2
	v_mov_b32_e32 v28, v2
	v_mov_b32_e32 v29, v2
	v_mov_b32_e32 v30, v2
	v_mov_b32_e32 v31, v2
	v_mov_b32_e32 v32, v2
	v_mov_b32_e32 v33, v2
	v_mov_b32_e32 v42, v2
	v_mov_b32_e32 v43, v2
	v_mov_b32_e32 v44, v2
	v_mov_b32_e32 v45, v2
	v_mov_b32_e32 v46, v2
	v_mov_b32_e32 v47, v2
	v_mov_b32_e32 v48, v2
	v_mov_b32_e32 v49, v2
	v_mov_b32_e32 v18, v2
	v_mov_b32_e32 v19, v2
	v_mov_b32_e32 v20, v2
	v_mov_b32_e32 v21, v2
	v_mov_b32_e32 v22, v2
	v_mov_b32_e32 v23, v2
	v_mov_b32_e32 v24, v2
	v_mov_b32_e32 v25, v2
	v_mov_b32_e32 v34, v2
	v_mov_b32_e32 v35, v2
	v_mov_b32_e32 v36, v2
	v_mov_b32_e32 v37, v2
	v_mov_b32_e32 v38, v2
	v_mov_b32_e32 v39, v2
	v_mov_b32_e32 v40, v2
	v_mov_b32_e32 v41, v2
	v_mov_b32_e32 v50, v2
	v_mov_b32_e32 v51, v2
	v_mov_b32_e32 v52, v2
	v_mov_b32_e32 v53, v2
	v_mov_b32_e32 v54, v2
	v_mov_b32_e32 v55, v2
	v_mov_b32_e32 v56, v2
	v_mov_b32_e32 v57, v2
	v_mov_b32_e32 v58, v2
	v_mov_b32_e32 v59, v2
	v_mov_b32_e32 v60, v2
	v_mov_b32_e32 v61, v2
	v_mov_b32_e32 v62, v2
	v_mov_b32_e32 v63, v2
	v_mov_b32_e32 v64, v2
	v_mov_b32_e32 v65, v2
	v_mov_b32_e32 v66, v2
	v_mov_b32_e32 v67, v2
	v_mov_b32_e32 v68, v2
	v_mov_b32_e32 v69, v2
	v_mov_b32_e32 v70, v2
	v_mov_b32_e32 v71, v2
	v_mov_b32_e32 v72, v2
	v_mov_b32_e32 v73, v2
	v_mov_b32_e32 v74, v2
	v_mov_b32_e32 v75, v2
	v_mov_b32_e32 v76, v2
	v_mov_b32_e32 v77, v2
	v_mov_b32_e32 v78, v2
	v_mov_b32_e32 v79, v2
	v_mov_b32_e32 v80, v2
	v_mov_b32_e32 v81, v2
	v_mov_b32_e32 v90, v2
	v_mov_b32_e32 v91, v2
	v_mov_b32_e32 v92, v2
	v_mov_b32_e32 v93, v2
	v_mov_b32_e32 v94, v2
	v_mov_b32_e32 v95, v2
	v_mov_b32_e32 v96, v2
	v_mov_b32_e32 v97, v2
	v_mov_b32_e32 v106, v2
	v_mov_b32_e32 v107, v2
	v_mov_b32_e32 v108, v2
	v_mov_b32_e32 v109, v2
	v_mov_b32_e32 v110, v2
	v_mov_b32_e32 v111, v2
	v_mov_b32_e32 v112, v2
	v_mov_b32_e32 v113, v2
	v_mov_b32_e32 v82, v2
	v_mov_b32_e32 v83, v2
	v_mov_b32_e32 v84, v2
	v_mov_b32_e32 v85, v2
	v_mov_b32_e32 v86, v2
	v_mov_b32_e32 v87, v2
	v_mov_b32_e32 v88, v2
	v_mov_b32_e32 v89, v2
	v_mov_b32_e32 v98, v2
	v_mov_b32_e32 v99, v2
	v_mov_b32_e32 v100, v2
	v_mov_b32_e32 v101, v2
	v_mov_b32_e32 v102, v2
	v_mov_b32_e32 v103, v2
	v_mov_b32_e32 v104, v2
	v_mov_b32_e32 v105, v2
	v_mov_b32_e32 v114, v2
	v_mov_b32_e32 v115, v2
	v_mov_b32_e32 v116, v2
	v_mov_b32_e32 v117, v2
	v_mov_b32_e32 v118, v2
	v_mov_b32_e32 v119, v2
	v_mov_b32_e32 v120, v2
	v_mov_b32_e32 v121, v2
	v_mov_b32_e32 v122, v2
	v_mov_b32_e32 v123, v2
	v_mov_b32_e32 v124, v2
	v_mov_b32_e32 v125, v2
	v_mov_b32_e32 v126, v2
	v_mov_b32_e32 v127, v2
	v_mov_b32_e32 v128, v2
	v_mov_b32_e32 v129, v2
	s_cmp_lg_u32 s101, 0
	s_cbranch_scc1 .Lx_P1_Tentry
	s_cmp_lg_u32 s52, 1
	s_cbranch_scc1 .LBB0_121
	s_add_i32 m0, s98, 0xc000
	s_nop 0
	global_load_lds_dwordx4 v130, s[34:35]
.LBB0_121:
	s_add_u32 s36, s34, 0xfff00080
	s_addc_u32 s37, s35, -1
	s_cmp_eq_u32 s58, 60
	s_cselect_b32 s39, s27, s37
	s_cselect_b32 s38, s54, s36
	s_cselect_b32 s37, s25, s57
	s_cselect_b32 s36, s55, s56
	ds_read_b128 v[150:153], v157 offset:0
	ds_read_b128 v[160:163], v157 offset:1024
	ds_read_b128 v[164:167], v157 offset:2048
	ds_read_b128 v[168:171], v157 offset:3072
	ds_read_b128 v[172:175], v158 offset:0
	ds_read_b128 v[176:179], v158 offset:1024
	ds_read_b128 v[180:183], v158 offset:2048
	ds_read_b128 v[184:187], v158 offset:3072
	ds_read_b128 v[188:191], v159 offset:0
	ds_read_b128 v[196:199], v159 offset:1024
	ds_read_b128 v[200:203], v159 offset:2048
	ds_read_b128 v[204:207], v159 offset:3072
	ds_read_b128 v[208:211], v159 offset:4096
	ds_read_b128 v[212:215], v159 offset:5120
	ds_read_b128 v[216:219], v159 offset:6144
	ds_read_b128 v[220:223], v159 offset:7168
	ds_read_b128 v[224:227], v159 offset:16384
	ds_read_b128 v[228:231], v159 offset:17408
	ds_read_b128 v[232:235], v159 offset:18432
	ds_read_b128 v[236:239], v159 offset:19456
	ds_read_b128 v[240:243], v159 offset:20480
	ds_read_b128 v[244:247], v159 offset:21504
	ds_read_b128 v[248:251], v159 offset:22528
	ds_read_b128 v[142:145], v159 offset:23552
	s_add_u32 s60, s56, 0xffff8000
	s_addc_u32 s61, s57, -1
	s_add_i32 m0, s98, 0x18000
	s_nop 0
	global_load_lds_dwordx4 v132, s[60:61]
	s_add_i32 m0, s98, 0x19000
	s_nop 0
	global_load_lds_dwordx4 v133, s[60:61]
	s_add_i32 m0, s98, 0x1a000
	s_nop 0
	global_load_lds_dwordx4 v136, s[60:61]
	s_add_i32 m0, s98, 0x1b000
	s_nop 0
	global_load_lds_dwordx4 v137, s[60:61]
	s_add_u32 s60, s60, 0x4000
	s_addc_u32 s61, s61, 0
	s_add_i32 m0, s98, 0x1c000
	s_nop 0
	global_load_lds_dwordx4 v132, s[60:61]
	s_add_i32 m0, s98, 0x1d000
	s_nop 0
	global_load_lds_dwordx4 v133, s[60:61]
	s_add_i32 m0, s98, 0x1e000
	s_nop 0
	global_load_lds_dwordx4 v136, s[60:61]
	s_add_i32 m0, s98, 0x1f000
	s_nop 0
	global_load_lds_dwordx4 v137, s[60:61]
	s_waitcnt lgkmcnt(0)
	s_barrier
; #define PG8_STAGE(bufoff, gbase, voff) do { _Pragma("unroll") for (int _i = 0; _i < 2; ++_i) \
;         __builtin_amdgcn_global_load_lds((const unsigned*)((const char*)(gbase) + (voff)[_i]), (PG8_LAS unsigned*)(lds + (bufoff) + ldsw + _i * 8192), 16, 0, 0); } while (0)
; #define PG8_LDA(dst, b, h) do { _Pragma("unroll") for (int m = 0; m < 4; ++m) _Pragma("unroll") for (int k = 0; k < 2; ++k) dst[m][k] = *(const PG8_LAS bf16x8*)(lds + PG8_SA(b, h) + aoff + m * 2048 + k * 1024); } while (0)
; #define PG8_LDB(dst, b, h) do { _Pragma("unroll") for (int n = 0; n < 2; ++n) _Pragma("unroll") for (int k = 0; k < 2; ++k) dst[n][k] = *(const PG8_LAS bf16x8*)(lds + PG8_SB(b, h) + boff + n * 2048 + k * 1024); } while (0)
; #define PG8_MMA(ai, bj, At, Bt) do { __builtin_amdgcn_s_setprio(1); _Pragma("unroll") for (int m = 0; m < 4; ++m) _Pragma("unroll") for (int n = 0; n < 2; ++n) _Pragma("unroll") for (int k = 0; k < 2; ++k) \
;         acc[ai][bj][m][n] = __builtin_amdgcn_mfma_f32_16x16x32_bf16(Bt[n][k], At[m][k], acc[ai][bj][m][n], 0, 0, 0); __builtin_amdgcn_s_setprio(0); } while (0)
; template <class Epi, class Sched, bool ALIGN_EPI = false, bool SP2 = false>
; __device__ __forceinline__ void gemm_phase(PG8_LAS unsigned char* lds, const Gemm g, const Sched& S, const Epi& E) {
;     ...
;             if constexpr (SP2) {
;             PG8_LDB(B0, 0, 0); PG8_LDB(B1, 0, 1); PG8_SCHED; PG8_LDA(At, 0, 0); PG8_STAGE(PG8_SA(1, 1), a1 + hstepA, voffA);
;             PG8_WAIT_V(8); PG8_WAIT_L(0); PG8_BAR; PG8_MMA(0, 0, At, B0); PG8_MMA(0, 1, At, B1); PG8_BAR; PG8_SCHED;
;             PG8_LDA(At, 0, 1); PG8_STAGE(PG8_SB(0, 0), b2, voffB); PG8_STAGE(PG8_SB(0, 1), b2 + hstepB, voffB); PG8_STAGE(PG8_SA(0, 0), a2, voffA);
;             PG8_WAIT_V(8); PG8_WAIT_L(0); PG8_BAR; PG8_MMA(1, 0, At, B0); PG8_MMA(1, 1, At, B1); PG8_BAR; PG8_SCHED;
;             PG8_LDB(B0, 1, 0); PG8_LDB(B1, 1, 1); PG8_SCHED; PG8_LDA(At, 1, 0); PG8_STAGE(PG8_SA(0, 1), a2 + hstepA, voffA);
;             PG8_WAIT_V(8); PG8_WAIT_L(0); PG8_BAR; PG8_MMA(0, 0, At, B0); PG8_MMA(0, 1, At, B1); PG8_BAR; PG8_SCHED;
;             PG8_LDA(At, 1, 1); PG8_STAGE(PG8_SB(1, 0), b3, voffB); PG8_STAGE(PG8_SB(1, 1), b3 + hstepB, voffB); PG8_STAGE(PG8_SA(1, 0), a3, voffA);
;             PG8_WAIT_V(8); PG8_WAIT_L(0); PG8_BAR; PG8_MMA(1, 0, At, B0); PG8_MMA(1, 1, At, B1); PG8_BAR; PG8_SCHED;
	s_setprio 1
	v_mfma_f32_16x16x32_bf16 v[126:129], v[150:153], v[188:191], v[126:129]
	v_mfma_f32_16x16x32_bf16 v[122:125], v[164:167], v[188:191], v[122:125]
	v_mfma_f32_16x16x32_bf16 v[118:121], v[150:153], v[200:203], v[118:121]
	v_mfma_f32_16x16x32_bf16 v[114:117], v[164:167], v[200:203], v[114:117]
	v_mfma_f32_16x16x32_bf16 v[102:105], v[150:153], v[208:211], v[102:105]
	v_mfma_f32_16x16x32_bf16 v[98:101], v[164:167], v[208:211], v[98:101]
	v_mfma_f32_16x16x32_bf16 v[86:89], v[150:153], v[216:219], v[86:89]
	v_mfma_f32_16x16x32_bf16 v[82:85], v[164:167], v[216:219], v[82:85]
	v_mfma_f32_16x16x32_bf16 v[126:129], v[160:163], v[196:199], v[126:129]
	v_mfma_f32_16x16x32_bf16 v[122:125], v[168:171], v[196:199], v[122:125]
	v_mfma_f32_16x16x32_bf16 v[118:121], v[160:163], v[204:207], v[118:121]
	v_mfma_f32_16x16x32_bf16 v[114:117], v[168:171], v[204:207], v[114:117]
	v_mfma_f32_16x16x32_bf16 v[102:105], v[160:163], v[212:215], v[102:105]
	v_mfma_f32_16x16x32_bf16 v[98:101], v[168:171], v[212:215], v[98:101]
	v_mfma_f32_16x16x32_bf16 v[86:89], v[160:163], v[220:223], v[86:89]
	v_mfma_f32_16x16x32_bf16 v[82:85], v[168:171], v[220:223], v[82:85]
	v_mfma_f32_16x16x32_bf16 v[110:113], v[172:175], v[188:191], v[110:113]
	v_mfma_f32_16x16x32_bf16 v[106:109], v[180:183], v[188:191], v[106:109]
	v_mfma_f32_16x16x32_bf16 v[94:97], v[172:175], v[200:203], v[94:97]
	v_mfma_f32_16x16x32_bf16 v[90:93], v[180:183], v[200:203], v[90:93]
	v_mfma_f32_16x16x32_bf16 v[78:81], v[172:175], v[208:211], v[78:81]
	v_mfma_f32_16x16x32_bf16 v[74:77], v[180:183], v[208:211], v[74:77]
	v_mfma_f32_16x16x32_bf16 v[70:73], v[172:175], v[216:219], v[70:73]
	v_mfma_f32_16x16x32_bf16 v[66:69], v[180:183], v[216:219], v[66:69]
	v_mfma_f32_16x16x32_bf16 v[110:113], v[176:179], v[196:199], v[110:113]
	v_mfma_f32_16x16x32_bf16 v[106:109], v[184:187], v[196:199], v[106:109]
	v_mfma_f32_16x16x32_bf16 v[94:97], v[176:179], v[204:207], v[94:97]
	v_mfma_f32_16x16x32_bf16 v[90:93], v[184:187], v[204:207], v[90:93]
	v_mfma_f32_16x16x32_bf16 v[78:81], v[176:179], v[212:215], v[78:81]
	v_mfma_f32_16x16x32_bf16 v[74:77], v[184:187], v[212:215], v[74:77]
	v_mfma_f32_16x16x32_bf16 v[70:73], v[176:179], v[220:223], v[70:73]
	v_mfma_f32_16x16x32_bf16 v[66:69], v[184:187], v[220:223], v[66:69]
	v_mfma_f32_16x16x32_bf16 v[62:65], v[150:153], v[224:227], v[62:65]
	v_mfma_f32_16x16x32_bf16 v[58:61], v[164:167], v[224:227], v[58:61]
	v_mfma_f32_16x16x32_bf16 v[54:57], v[150:153], v[232:235], v[54:57]
	v_mfma_f32_16x16x32_bf16 v[50:53], v[164:167], v[232:235], v[50:53]
	v_mfma_f32_16x16x32_bf16 v[38:41], v[150:153], v[240:243], v[38:41]
	v_mfma_f32_16x16x32_bf16 v[34:37], v[164:167], v[240:243], v[34:37]
	v_mfma_f32_16x16x32_bf16 v[22:25], v[150:153], v[248:251], v[22:25]
	v_mfma_f32_16x16x32_bf16 v[18:21], v[164:167], v[248:251], v[18:21]
	v_mfma_f32_16x16x32_bf16 v[62:65], v[160:163], v[228:231], v[62:65]
	v_mfma_f32_16x16x32_bf16 v[58:61], v[168:171], v[228:231], v[58:61]
	v_mfma_f32_16x16x32_bf16 v[54:57], v[160:163], v[236:239], v[54:57]
	v_mfma_f32_16x16x32_bf16 v[50:53], v[168:171], v[236:239], v[50:53]
	v_mfma_f32_16x16x32_bf16 v[38:41], v[160:163], v[244:247], v[38:41]
	v_mfma_f32_16x16x32_bf16 v[34:37], v[168:171], v[244:247], v[34:37]
	v_mfma_f32_16x16x32_bf16 v[22:25], v[160:163], v[142:145], v[22:25]
	v_mfma_f32_16x16x32_bf16 v[18:21], v[168:171], v[142:145], v[18:21]
	v_mfma_f32_16x16x32_bf16 v[46:49], v[172:175], v[224:227], v[46:49]
	v_mfma_f32_16x16x32_bf16 v[42:45], v[180:183], v[224:227], v[42:45]
	v_mfma_f32_16x16x32_bf16 v[30:33], v[172:175], v[232:235], v[30:33]
	v_mfma_f32_16x16x32_bf16 v[26:29], v[180:183], v[232:235], v[26:29]
	v_mfma_f32_16x16x32_bf16 v[14:17], v[172:175], v[240:243], v[14:17]
	v_mfma_f32_16x16x32_bf16 v[10:13], v[180:183], v[240:243], v[10:13]
	v_mfma_f32_16x16x32_bf16 v[6:9], v[172:175], v[248:251], v[6:9]
	v_mfma_f32_16x16x32_bf16 v[2:5], v[180:183], v[248:251], v[2:5]
	v_mfma_f32_16x16x32_bf16 v[46:49], v[176:179], v[228:231], v[46:49]
	v_mfma_f32_16x16x32_bf16 v[42:45], v[184:187], v[228:231], v[42:45]
	v_mfma_f32_16x16x32_bf16 v[30:33], v[176:179], v[236:239], v[30:33]
	v_mfma_f32_16x16x32_bf16 v[26:29], v[184:187], v[236:239], v[26:29]
	v_mfma_f32_16x16x32_bf16 v[14:17], v[176:179], v[244:247], v[14:17]
	v_mfma_f32_16x16x32_bf16 v[10:13], v[184:187], v[244:247], v[10:13]
	v_mfma_f32_16x16x32_bf16 v[6:9], v[176:179], v[142:145], v[6:9]
	v_mfma_f32_16x16x32_bf16 v[2:5], v[184:187], v[142:145], v[2:5]
	s_setprio 0
	s_waitcnt vmcnt(0)
	s_barrier
	ds_read_b128 v[150:153], v157 offset:32768
	ds_read_b128 v[160:163], v157 offset:33792
	ds_read_b128 v[164:167], v157 offset:34816
	ds_read_b128 v[168:171], v157 offset:35840
	ds_read_b128 v[172:175], v158 offset:32768
	ds_read_b128 v[176:179], v158 offset:33792
	ds_read_b128 v[180:183], v158 offset:34816
	ds_read_b128 v[184:187], v158 offset:35840
	ds_read_b128 v[188:191], v159 offset:32768
	ds_read_b128 v[196:199], v159 offset:33792
	ds_read_b128 v[200:203], v159 offset:34816
	ds_read_b128 v[204:207], v159 offset:35840
	ds_read_b128 v[208:211], v159 offset:36864
	ds_read_b128 v[212:215], v159 offset:37888
	ds_read_b128 v[216:219], v159 offset:38912
	ds_read_b128 v[220:223], v159 offset:39936
	ds_read_b128 v[224:227], v159 offset:49152
	ds_read_b128 v[228:231], v159 offset:50176
	ds_read_b128 v[232:235], v159 offset:51200
	ds_read_b128 v[236:239], v159 offset:52224
	ds_read_b128 v[240:243], v159 offset:53248
	ds_read_b128 v[244:247], v159 offset:54272
	ds_read_b128 v[248:251], v159 offset:55296
	ds_read_b128 v[142:145], v159 offset:56320
	s_add_i32 m0, s98, 0x10000
	s_nop 0
	global_load_lds_dwordx4 v132, s[36:37]
	s_add_i32 m0, s98, 0x11000
	s_nop 0
	global_load_lds_dwordx4 v133, s[36:37]
	s_add_i32 m0, s98, 0x12000
	s_nop 0
	global_load_lds_dwordx4 v136, s[36:37]
	s_add_i32 m0, s98, 0x13000
	s_nop 0
	global_load_lds_dwordx4 v137, s[36:37]
	s_add_u32 s60, s36, 0x4000
	s_addc_u32 s61, s37, 0
	s_add_i32 m0, s98, 0x14000
	s_nop 0
	global_load_lds_dwordx4 v132, s[60:61]
	s_add_i32 m0, s98, 0x15000
	s_nop 0
	global_load_lds_dwordx4 v133, s[60:61]
	s_add_i32 m0, s98, 0x16000
	s_nop 0
	global_load_lds_dwordx4 v136, s[60:61]
	s_add_i32 m0, s98, 0x17000
	s_nop 0
	global_load_lds_dwordx4 v137, s[60:61]
	s_waitcnt lgkmcnt(0)
	s_barrier
; #define PG8_STAGE(bufoff, gbase, voff) do { _Pragma("unroll") for (int _i = 0; _i < 2; ++_i) \
;         __builtin_amdgcn_global_load_lds((const unsigned*)((const char*)(gbase) + (voff)[_i]), (PG8_LAS unsigned*)(lds + (bufoff) + ldsw + _i * 8192), 16, 0, 0); } while (0)
; #define PG8_LDA(dst, b, h) do { _Pragma("unroll") for (int m = 0; m < 4; ++m) _Pragma("unroll") for (int k = 0; k < 2; ++k) dst[m][k] = *(const PG8_LAS bf16x8*)(lds + PG8_SA(b, h) + aoff + m * 2048 + k * 1024); } while (0)
; #define PG8_LDB(dst, b, h) do { _Pragma("unroll") for (int n = 0; n < 2; ++n) _Pragma("unroll") for (int k = 0; k < 2; ++k) dst[n][k] = *(const PG8_LAS bf16x8*)(lds + PG8_SB(b, h) + boff + n * 2048 + k * 1024); } while (0)
; template <class Epi, class Sched, bool ALIGN_EPI = false, bool SP2 = false>
; __device__ __forceinline__ void gemm_phase(PG8_LAS unsigned char* lds, const Gemm g, const Sched& S, const Epi& E) {
;     ...
;         for (int t = 0; t < nt; t += 2) {
;             const bool last = (t == nt - 2);
;             const char* a1 = cA + (size_t)(t + 1) * kstep;
;             const char* a2 = last ? nA : cA + (size_t)(t + 2) * kstep; const char* b2 = last ? nB : cB + (size_t)(t + 2) * kstepB;
;             const char* a3 = a2 + kstep; const char* b3 = b2 + kstepB;
;             if (last && has_next) S.a_ready(nxt);
;             if constexpr (SP2) {
;             PG8_LDB(B0, 0, 0); PG8_LDB(B1, 0, 1); PG8_SCHED; PG8_LDA(At, 0, 0); PG8_STAGE(PG8_SA(1, 1), a1 + hstepA, voffA);
;             PG8_WAIT_V(8); PG8_WAIT_L(0); PG8_BAR; PG8_MMA(0, 0, At, B0); PG8_MMA(0, 1, At, B1); PG8_BAR; PG8_SCHED;
;             PG8_LDA(At, 0, 1); PG8_STAGE(PG8_SB(0, 0), b2, voffB); PG8_STAGE(PG8_SB(0, 1), b2 + hstepB, voffB); PG8_STAGE(PG8_SA(0, 0), a2, voffA);
;             PG8_WAIT_V(8); PG8_WAIT_L(0); PG8_BAR; PG8_MMA(1, 0, At, B0); PG8_MMA(1, 1, At, B1); PG8_BAR; PG8_SCHED;
;             PG8_LDB(B0, 1, 0); PG8_LDB(B1, 1, 1); PG8_SCHED; PG8_LDA(At, 1, 0); PG8_STAGE(PG8_SA(0, 1), a2 + hstepA, voffA);
;             PG8_WAIT_V(8); PG8_WAIT_L(0); PG8_BAR; PG8_MMA(0, 0, At, B0); PG8_MMA(0, 1, At, B1); PG8_BAR; PG8_SCHED;
;             PG8_LDA(At, 1, 1); PG8_STAGE(PG8_SB(1, 0), b3, voffB); PG8_STAGE(PG8_SB(1, 1), b3 + hstepB, voffB); PG8_STAGE(PG8_SA(1, 0), a3, voffA);
;             PG8_WAIT_V(8); PG8_WAIT_L(0); PG8_BAR; PG8_MMA(1, 0, At, B0); PG8_MMA(1, 1, At, B1); PG8_BAR; PG8_SCHED;
	s_setprio 1
	v_mfma_f32_16x16x32_bf16 v[126:129], v[150:153], v[188:191], v[126:129]
	v_mfma_f32_16x16x32_bf16 v[122:125], v[164:167], v[188:191], v[122:125]
	v_mfma_f32_16x16x32_bf16 v[118:121], v[150:153], v[200:203], v[118:121]
	v_mfma_f32_16x16x32_bf16 v[114:117], v[164:167], v[200:203], v[114:117]
	v_mfma_f32_16x16x32_bf16 v[102:105], v[150:153], v[208:211], v[102:105]
	v_mfma_f32_16x16x32_bf16 v[98:101], v[164:167], v[208:211], v[98:101]
	v_mfma_f32_16x16x32_bf16 v[86:89], v[150:153], v[216:219], v[86:89]
	v_mfma_f32_16x16x32_bf16 v[82:85], v[164:167], v[216:219], v[82:85]
	v_mfma_f32_16x16x32_bf16 v[126:129], v[160:163], v[196:199], v[126:129]
	v_mfma_f32_16x16x32_bf16 v[122:125], v[168:171], v[196:199], v[122:125]
	v_mfma_f32_16x16x32_bf16 v[118:121], v[160:163], v[204:207], v[118:121]
	v_mfma_f32_16x16x32_bf16 v[114:117], v[168:171], v[204:207], v[114:117]
	v_mfma_f32_16x16x32_bf16 v[102:105], v[160:163], v[212:215], v[102:105]
	v_mfma_f32_16x16x32_bf16 v[98:101], v[168:171], v[212:215], v[98:101]
	v_mfma_f32_16x16x32_bf16 v[86:89], v[160:163], v[220:223], v[86:89]
	v_mfma_f32_16x16x32_bf16 v[82:85], v[168:171], v[220:223], v[82:85]
	v_mfma_f32_16x16x32_bf16 v[110:113], v[172:175], v[188:191], v[110:113]
	v_mfma_f32_16x16x32_bf16 v[106:109], v[180:183], v[188:191], v[106:109]
	v_mfma_f32_16x16x32_bf16 v[94:97], v[172:175], v[200:203], v[94:97]
	v_mfma_f32_16x16x32_bf16 v[90:93], v[180:183], v[200:203], v[90:93]
	v_mfma_f32_16x16x32_bf16 v[78:81], v[172:175], v[208:211], v[78:81]
	v_mfma_f32_16x16x32_bf16 v[74:77], v[180:183], v[208:211], v[74:77]
	v_mfma_f32_16x16x32_bf16 v[70:73], v[172:175], v[216:219], v[70:73]
	v_mfma_f32_16x16x32_bf16 v[66:69], v[180:183], v[216:219], v[66:69]
	v_mfma_f32_16x16x32_bf16 v[110:113], v[176:179], v[196:199], v[110:113]
	v_mfma_f32_16x16x32_bf16 v[106:109], v[184:187], v[196:199], v[106:109]
	v_mfma_f32_16x16x32_bf16 v[94:97], v[176:179], v[204:207], v[94:97]
	v_mfma_f32_16x16x32_bf16 v[90:93], v[184:187], v[204:207], v[90:93]
	v_mfma_f32_16x16x32_bf16 v[78:81], v[176:179], v[212:215], v[78:81]
	v_mfma_f32_16x16x32_bf16 v[74:77], v[184:187], v[212:215], v[74:77]
	v_mfma_f32_16x16x32_bf16 v[70:73], v[176:179], v[220:223], v[70:73]
	v_mfma_f32_16x16x32_bf16 v[66:69], v[184:187], v[220:223], v[66:69]
	v_mfma_f32_16x16x32_bf16 v[62:65], v[150:153], v[224:227], v[62:65]
	v_mfma_f32_16x16x32_bf16 v[58:61], v[164:167], v[224:227], v[58:61]
	v_mfma_f32_16x16x32_bf16 v[54:57], v[150:153], v[232:235], v[54:57]
	v_mfma_f32_16x16x32_bf16 v[50:53], v[164:167], v[232:235], v[50:53]
	v_mfma_f32_16x16x32_bf16 v[38:41], v[150:153], v[240:243], v[38:41]
	v_mfma_f32_16x16x32_bf16 v[34:37], v[164:167], v[240:243], v[34:37]
	v_mfma_f32_16x16x32_bf16 v[22:25], v[150:153], v[248:251], v[22:25]
	v_mfma_f32_16x16x32_bf16 v[18:21], v[164:167], v[248:251], v[18:21]
	v_mfma_f32_16x16x32_bf16 v[62:65], v[160:163], v[228:231], v[62:65]
	v_mfma_f32_16x16x32_bf16 v[58:61], v[168:171], v[228:231], v[58:61]
	v_mfma_f32_16x16x32_bf16 v[54:57], v[160:163], v[236:239], v[54:57]
	v_mfma_f32_16x16x32_bf16 v[50:53], v[168:171], v[236:239], v[50:53]
	v_mfma_f32_16x16x32_bf16 v[38:41], v[160:163], v[244:247], v[38:41]
	v_mfma_f32_16x16x32_bf16 v[34:37], v[168:171], v[244:247], v[34:37]
	v_mfma_f32_16x16x32_bf16 v[22:25], v[160:163], v[142:145], v[22:25]
	v_mfma_f32_16x16x32_bf16 v[18:21], v[168:171], v[142:145], v[18:21]
	v_mfma_f32_16x16x32_bf16 v[46:49], v[172:175], v[224:227], v[46:49]
	v_mfma_f32_16x16x32_bf16 v[42:45], v[180:183], v[224:227], v[42:45]
	v_mfma_f32_16x16x32_bf16 v[30:33], v[172:175], v[232:235], v[30:33]
	v_mfma_f32_16x16x32_bf16 v[26:29], v[180:183], v[232:235], v[26:29]
	v_mfma_f32_16x16x32_bf16 v[14:17], v[172:175], v[240:243], v[14:17]
	v_mfma_f32_16x16x32_bf16 v[10:13], v[180:183], v[240:243], v[10:13]
	v_mfma_f32_16x16x32_bf16 v[6:9], v[172:175], v[248:251], v[6:9]
	v_mfma_f32_16x16x32_bf16 v[2:5], v[180:183], v[248:251], v[2:5]
	v_mfma_f32_16x16x32_bf16 v[46:49], v[176:179], v[228:231], v[46:49]
	v_mfma_f32_16x16x32_bf16 v[42:45], v[184:187], v[228:231], v[42:45]
	v_mfma_f32_16x16x32_bf16 v[30:33], v[176:179], v[236:239], v[30:33]
	v_mfma_f32_16x16x32_bf16 v[26:29], v[184:187], v[236:239], v[26:29]
	v_mfma_f32_16x16x32_bf16 v[14:17], v[176:179], v[244:247], v[14:17]
	v_mfma_f32_16x16x32_bf16 v[10:13], v[184:187], v[244:247], v[10:13]
	v_mfma_f32_16x16x32_bf16 v[6:9], v[176:179], v[142:145], v[6:9]
	v_mfma_f32_16x16x32_bf16 v[2:5], v[184:187], v[142:145], v[2:5]
	s_setprio 0
	s_waitcnt vmcnt(0)
	s_barrier
	s_add_i32 s58, s58, 2
	s_add_u32 s56, s56, 0x10000
	s_addc_u32 s57, s57, 0
	s_add_u32 s34, s34, 0x100
	s_addc_u32 s35, s35, 0
	s_cmp_gt_u32 s58, 61
	s_cbranch_scc0 .LBB0_121
	s_branch .Lx_P1_exit
.Lx_P1_Tentry:
	s_cmp_lg_u32 s52, 1
	s_cbranch_scc1 .Lx_P1_Tloop
	s_add_i32 m0, s98, 0xd000
	s_nop 0
	global_load_lds_dwordx4 v131, s[34:35]
; #define PG8_STAGE(bufoff, gbase, voff) do { _Pragma("unroll") for (int _i = 0; _i < 2; ++_i) \
;         __builtin_amdgcn_global_load_lds((const unsigned*)((const char*)(gbase) + (voff)[_i]), (PG8_LAS unsigned*)(lds + (bufoff) + ldsw + _i * 8192), 16, 0, 0); } while (0)
; #define PG8_LDA(dst, b, h) do { _Pragma("unroll") for (int m = 0; m < 4; ++m) _Pragma("unroll") for (int k = 0; k < 2; ++k) dst[m][k] = *(const PG8_LAS bf16x8*)(lds + PG8_SA(b, h) + aoff + m * 2048 + k * 1024); } while (0)
; #define PG8_LDB(dst, b, h) do { _Pragma("unroll") for (int n = 0; n < 2; ++n) _Pragma("unroll") for (int k = 0; k < 2; ++k) dst[n][k] = *(const PG8_LAS bf16x8*)(lds + PG8_SB(b, h) + boff + n * 2048 + k * 1024); } while (0)
; template <class Epi, class Sched, bool ALIGN_EPI = false, bool SP2 = false>
; __device__ __forceinline__ void gemm_phase(PG8_LAS unsigned char* lds, const Gemm g, const Sched& S, const Epi& E) {
;     ...
;         for (int t = 0; t < nt; t += 2) {
;             const bool last = (t == nt - 2);
;             const char* a1 = cA + (size_t)(t + 1) * kstep;
;             const char* a2 = last ? nA : cA + (size_t)(t + 2) * kstep; const char* b2 = last ? nB : cB + (size_t)(t + 2) * kstepB;
;             const char* a3 = a2 + kstep; const char* b3 = b2 + kstepB;
;             if (last && has_next) S.a_ready(nxt);
;             if constexpr (SP2) {
;             PG8_LDB(B0, 0, 0); PG8_LDB(B1, 0, 1); PG8_SCHED; PG8_LDA(At, 0, 0); PG8_STAGE(PG8_SA(1, 1), a1 + hstepA, voffA);
;             PG8_WAIT_V(8); PG8_WAIT_L(0); PG8_BAR; PG8_MMA(0, 0, At, B0); PG8_MMA(0, 1, At, B1); PG8_BAR; PG8_SCHED;
;             PG8_LDA(At, 0, 1); PG8_STAGE(PG8_SB(0, 0), b2, voffB); PG8_STAGE(PG8_SB(0, 1), b2 + hstepB, voffB); PG8_STAGE(PG8_SA(0, 0), a2, voffA);
;             PG8_WAIT_V(8); PG8_WAIT_L(0); PG8_BAR; PG8_MMA(1, 0, At, B0); PG8_MMA(1, 1, At, B1); PG8_BAR; PG8_SCHED;
;             PG8_LDB(B0, 1, 0); PG8_LDB(B1, 1, 1); PG8_SCHED; PG8_LDA(At, 1, 0); PG8_STAGE(PG8_SA(0, 1), a2 + hstepA, voffA);
;             PG8_WAIT_V(8); PG8_WAIT_L(0); PG8_BAR; PG8_MMA(0, 0, At, B0); PG8_MMA(0, 1, At, B1); PG8_BAR; PG8_SCHED;
;             PG8_LDA(At, 1, 1); PG8_STAGE(PG8_SB(1, 0), b3, voffB); PG8_STAGE(PG8_SB(1, 1), b3 + hstepB, voffB); PG8_STAGE(PG8_SA(1, 0), a3, voffA);
;             PG8_WAIT_V(8); PG8_WAIT_L(0); PG8_BAR; PG8_MMA(1, 0, At, B0); PG8_MMA(1, 1, At, B1); PG8_BAR; PG8_SCHED;
.Lx_P1_Tloop:
	s_add_u32 s36, s34, 0xfff00080
	s_addc_u32 s37, s35, -1
	s_cmp_eq_u32 s58, 60
	s_cselect_b32 s39, s27, s37
	s_cselect_b32 s38, s54, s36
	s_cselect_b32 s37, s25, s57
	s_cselect_b32 s36, s55, s56
	ds_read_b128 v[150:153], v157 offset:0
	ds_read_b128 v[160:163], v157 offset:1024
	ds_read_b128 v[164:167], v157 offset:2048
	ds_read_b128 v[168:171], v157 offset:3072
	ds_read_b128 v[172:175], v158 offset:0
	ds_read_b128 v[176:179], v158 offset:1024
	ds_read_b128 v[180:183], v158 offset:2048
	ds_read_b128 v[184:187], v158 offset:3072
	ds_read_b128 v[188:191], v159 offset:0
	ds_read_b128 v[196:199], v159 offset:1024
	ds_read_b128 v[200:203], v159 offset:2048
	ds_read_b128 v[204:207], v159 offset:3072
	ds_read_b128 v[208:211], v159 offset:4096
	ds_read_b128 v[212:215], v159 offset:5120
	ds_read_b128 v[216:219], v159 offset:6144
	ds_read_b128 v[220:223], v159 offset:7168
	ds_read_b128 v[224:227], v159 offset:16384
	ds_read_b128 v[228:231], v159 offset:17408
	ds_read_b128 v[232:235], v159 offset:18432
	ds_read_b128 v[236:239], v159 offset:19456
	ds_read_b128 v[240:243], v159 offset:20480
	ds_read_b128 v[244:247], v159 offset:21504
	ds_read_b128 v[248:251], v159 offset:22528
	ds_read_b128 v[142:145], v159 offset:23552
	s_add_u32 s60, s34, 0xfff00000
	s_addc_u32 s61, s35, -1
	s_add_i32 m0, s98, 0xa000
	s_nop 0
	global_load_lds_dwordx4 v134, s[60:61]
	s_add_i32 m0, s98, 0xb000
	s_nop 0
	global_load_lds_dwordx4 v135, s[60:61]
	s_add_i32 m0, s98, 0xe000
	s_nop 0
	global_load_lds_dwordx4 v134, s[34:35]
	s_add_i32 m0, s98, 0xf000
	s_nop 0
	global_load_lds_dwordx4 v135, s[34:35]
	s_add_u32 s60, s38, 0x100000
	s_addc_u32 s61, s39, 0
	s_add_i32 m0, s98, 0x0
	s_nop 0
	global_load_lds_dwordx4 v130, s[38:39]
	s_add_i32 m0, s98, 0x1000
	s_nop 0
	global_load_lds_dwordx4 v131, s[38:39]
	s_add_i32 m0, s98, 0x4000
	s_nop 0
	global_load_lds_dwordx4 v130, s[60:61]
	s_add_i32 m0, s98, 0x5000
	s_nop 0
	global_load_lds_dwordx4 v131, s[60:61]
	s_waitcnt vmcnt(8)
	s_waitcnt lgkmcnt(0)
	s_barrier
	s_setprio 1
	v_mfma_f32_16x16x32_bf16 v[126:129], v[150:153], v[188:191], v[126:129]
	v_mfma_f32_16x16x32_bf16 v[122:125], v[164:167], v[188:191], v[122:125]
	v_mfma_f32_16x16x32_bf16 v[118:121], v[150:153], v[200:203], v[118:121]
	v_mfma_f32_16x16x32_bf16 v[114:117], v[164:167], v[200:203], v[114:117]
	v_mfma_f32_16x16x32_bf16 v[102:105], v[150:153], v[208:211], v[102:105]
	v_mfma_f32_16x16x32_bf16 v[98:101], v[164:167], v[208:211], v[98:101]
	v_mfma_f32_16x16x32_bf16 v[86:89], v[150:153], v[216:219], v[86:89]
	v_mfma_f32_16x16x32_bf16 v[82:85], v[164:167], v[216:219], v[82:85]
	v_mfma_f32_16x16x32_bf16 v[126:129], v[160:163], v[196:199], v[126:129]
	v_mfma_f32_16x16x32_bf16 v[122:125], v[168:171], v[196:199], v[122:125]
	v_mfma_f32_16x16x32_bf16 v[118:121], v[160:163], v[204:207], v[118:121]
	v_mfma_f32_16x16x32_bf16 v[114:117], v[168:171], v[204:207], v[114:117]
	v_mfma_f32_16x16x32_bf16 v[102:105], v[160:163], v[212:215], v[102:105]
	v_mfma_f32_16x16x32_bf16 v[98:101], v[168:171], v[212:215], v[98:101]
	v_mfma_f32_16x16x32_bf16 v[86:89], v[160:163], v[220:223], v[86:89]
	v_mfma_f32_16x16x32_bf16 v[82:85], v[168:171], v[220:223], v[82:85]
	v_mfma_f32_16x16x32_bf16 v[110:113], v[172:175], v[188:191], v[110:113]
	v_mfma_f32_16x16x32_bf16 v[106:109], v[180:183], v[188:191], v[106:109]
	v_mfma_f32_16x16x32_bf16 v[94:97], v[172:175], v[200:203], v[94:97]
	v_mfma_f32_16x16x32_bf16 v[90:93], v[180:183], v[200:203], v[90:93]
	v_mfma_f32_16x16x32_bf16 v[78:81], v[172:175], v[208:211], v[78:81]
	v_mfma_f32_16x16x32_bf16 v[74:77], v[180:183], v[208:211], v[74:77]
	v_mfma_f32_16x16x32_bf16 v[70:73], v[172:175], v[216:219], v[70:73]
	v_mfma_f32_16x16x32_bf16 v[66:69], v[180:183], v[216:219], v[66:69]
	v_mfma_f32_16x16x32_bf16 v[110:113], v[176:179], v[196:199], v[110:113]
	v_mfma_f32_16x16x32_bf16 v[106:109], v[184:187], v[196:199], v[106:109]
	v_mfma_f32_16x16x32_bf16 v[94:97], v[176:179], v[204:207], v[94:97]
	v_mfma_f32_16x16x32_bf16 v[90:93], v[184:187], v[204:207], v[90:93]
	v_mfma_f32_16x16x32_bf16 v[78:81], v[176:179], v[212:215], v[78:81]
	v_mfma_f32_16x16x32_bf16 v[74:77], v[184:187], v[212:215], v[74:77]
	v_mfma_f32_16x16x32_bf16 v[70:73], v[176:179], v[220:223], v[70:73]
	v_mfma_f32_16x16x32_bf16 v[66:69], v[184:187], v[220:223], v[66:69]
	v_mfma_f32_16x16x32_bf16 v[62:65], v[150:153], v[224:227], v[62:65]
	v_mfma_f32_16x16x32_bf16 v[58:61], v[164:167], v[224:227], v[58:61]
	v_mfma_f32_16x16x32_bf16 v[54:57], v[150:153], v[232:235], v[54:57]
	v_mfma_f32_16x16x32_bf16 v[50:53], v[164:167], v[232:235], v[50:53]
	v_mfma_f32_16x16x32_bf16 v[38:41], v[150:153], v[240:243], v[38:41]
	v_mfma_f32_16x16x32_bf16 v[34:37], v[164:167], v[240:243], v[34:37]
	v_mfma_f32_16x16x32_bf16 v[22:25], v[150:153], v[248:251], v[22:25]
	v_mfma_f32_16x16x32_bf16 v[18:21], v[164:167], v[248:251], v[18:21]
	v_mfma_f32_16x16x32_bf16 v[62:65], v[160:163], v[228:231], v[62:65]
	v_mfma_f32_16x16x32_bf16 v[58:61], v[168:171], v[228:231], v[58:61]
	v_mfma_f32_16x16x32_bf16 v[54:57], v[160:163], v[236:239], v[54:57]
	v_mfma_f32_16x16x32_bf16 v[50:53], v[168:171], v[236:239], v[50:53]
	v_mfma_f32_16x16x32_bf16 v[38:41], v[160:163], v[244:247], v[38:41]
	v_mfma_f32_16x16x32_bf16 v[34:37], v[168:171], v[244:247], v[34:37]
	v_mfma_f32_16x16x32_bf16 v[22:25], v[160:163], v[142:145], v[22:25]
	v_mfma_f32_16x16x32_bf16 v[18:21], v[168:171], v[142:145], v[18:21]
	v_mfma_f32_16x16x32_bf16 v[46:49], v[172:175], v[224:227], v[46:49]
	v_mfma_f32_16x16x32_bf16 v[42:45], v[180:183], v[224:227], v[42:45]
	v_mfma_f32_16x16x32_bf16 v[30:33], v[172:175], v[232:235], v[30:33]
	v_mfma_f32_16x16x32_bf16 v[26:29], v[180:183], v[232:235], v[26:29]
	v_mfma_f32_16x16x32_bf16 v[14:17], v[172:175], v[240:243], v[14:17]
	v_mfma_f32_16x16x32_bf16 v[10:13], v[180:183], v[240:243], v[10:13]
	v_mfma_f32_16x16x32_bf16 v[6:9], v[172:175], v[248:251], v[6:9]
	v_mfma_f32_16x16x32_bf16 v[2:5], v[180:183], v[248:251], v[2:5]
	v_mfma_f32_16x16x32_bf16 v[46:49], v[176:179], v[228:231], v[46:49]
	v_mfma_f32_16x16x32_bf16 v[42:45], v[184:187], v[228:231], v[42:45]
	v_mfma_f32_16x16x32_bf16 v[30:33], v[176:179], v[236:239], v[30:33]
	v_mfma_f32_16x16x32_bf16 v[26:29], v[184:187], v[236:239], v[26:29]
	v_mfma_f32_16x16x32_bf16 v[14:17], v[176:179], v[244:247], v[14:17]
	v_mfma_f32_16x16x32_bf16 v[10:13], v[184:187], v[244:247], v[10:13]
	v_mfma_f32_16x16x32_bf16 v[6:9], v[176:179], v[142:145], v[6:9]
	v_mfma_f32_16x16x32_bf16 v[2:5], v[184:187], v[142:145], v[2:5]
	s_setprio 0
	s_waitcnt vmcnt(4)
	s_barrier
; #define PG8_STAGE(bufoff, gbase, voff) do { _Pragma("unroll") for (int _i = 0; _i < 2; ++_i) \
;         __builtin_amdgcn_global_load_lds((const unsigned*)((const char*)(gbase) + (voff)[_i]), (PG8_LAS unsigned*)(lds + (bufoff) + ldsw + _i * 8192), 16, 0, 0); } while (0)
; #define PG8_LDA(dst, b, h) do { _Pragma("unroll") for (int m = 0; m < 4; ++m) _Pragma("unroll") for (int k = 0; k < 2; ++k) dst[m][k] = *(const PG8_LAS bf16x8*)(lds + PG8_SA(b, h) + aoff + m * 2048 + k * 1024); } while (0)
; #define PG8_LDB(dst, b, h) do { _Pragma("unroll") for (int n = 0; n < 2; ++n) _Pragma("unroll") for (int k = 0; k < 2; ++k) dst[n][k] = *(const PG8_LAS bf16x8*)(lds + PG8_SB(b, h) + boff + n * 2048 + k * 1024); } while (0)
; template <class Epi, class Sched, bool ALIGN_EPI = false, bool SP2 = false>
; __device__ __forceinline__ void gemm_phase(PG8_LAS unsigned char* lds, const Gemm g, const Sched& S, const Epi& E) {
;     ...
;         for (int t = 0; t < nt; t += 2) {
;             const bool last = (t == nt - 2);
;             const char* a1 = cA + (size_t)(t + 1) * kstep;
;             const char* a2 = last ? nA : cA + (size_t)(t + 2) * kstep; const char* b2 = last ? nB : cB + (size_t)(t + 2) * kstepB;
;             const char* a3 = a2 + kstep; const char* b3 = b2 + kstepB;
;             if (last && has_next) S.a_ready(nxt);
;             if constexpr (SP2) {
;             PG8_LDB(B0, 0, 0); PG8_LDB(B1, 0, 1); PG8_SCHED; PG8_LDA(At, 0, 0); PG8_STAGE(PG8_SA(1, 1), a1 + hstepA, voffA);
;             PG8_WAIT_V(8); PG8_WAIT_L(0); PG8_BAR; PG8_MMA(0, 0, At, B0); PG8_MMA(0, 1, At, B1); PG8_BAR; PG8_SCHED;
;             PG8_LDA(At, 0, 1); PG8_STAGE(PG8_SB(0, 0), b2, voffB); PG8_STAGE(PG8_SB(0, 1), b2 + hstepB, voffB); PG8_STAGE(PG8_SA(0, 0), a2, voffA);
;             PG8_WAIT_V(8); PG8_WAIT_L(0); PG8_BAR; PG8_MMA(1, 0, At, B0); PG8_MMA(1, 1, At, B1); PG8_BAR; PG8_SCHED;
;             PG8_LDB(B0, 1, 0); PG8_LDB(B1, 1, 1); PG8_SCHED; PG8_LDA(At, 1, 0); PG8_STAGE(PG8_SA(0, 1), a2 + hstepA, voffA);
;             PG8_WAIT_V(8); PG8_WAIT_L(0); PG8_BAR; PG8_MMA(0, 0, At, B0); PG8_MMA(0, 1, At, B1); PG8_BAR; PG8_SCHED;
;             PG8_LDA(At, 1, 1); PG8_STAGE(PG8_SB(1, 0), b3, voffB); PG8_STAGE(PG8_SB(1, 1), b3 + hstepB, voffB); PG8_STAGE(PG8_SA(1, 0), a3, voffA);
;             PG8_WAIT_V(8); PG8_WAIT_L(0); PG8_BAR; PG8_MMA(1, 0, At, B0); PG8_MMA(1, 1, At, B1); PG8_BAR; PG8_SCHED;
	ds_read_b128 v[150:153], v157 offset:32768
	ds_read_b128 v[160:163], v157 offset:33792
	ds_read_b128 v[164:167], v157 offset:34816
	ds_read_b128 v[168:171], v157 offset:35840
	ds_read_b128 v[172:175], v158 offset:32768
	ds_read_b128 v[176:179], v158 offset:33792
	ds_read_b128 v[180:183], v158 offset:34816
	ds_read_b128 v[184:187], v158 offset:35840
	ds_read_b128 v[188:191], v159 offset:32768
	ds_read_b128 v[196:199], v159 offset:33792
	ds_read_b128 v[200:203], v159 offset:34816
	ds_read_b128 v[204:207], v159 offset:35840
	ds_read_b128 v[208:211], v159 offset:36864
	ds_read_b128 v[212:215], v159 offset:37888
	ds_read_b128 v[216:219], v159 offset:38912
	ds_read_b128 v[220:223], v159 offset:39936
	ds_read_b128 v[224:227], v159 offset:49152
	ds_read_b128 v[228:231], v159 offset:50176
	ds_read_b128 v[232:235], v159 offset:51200
	ds_read_b128 v[236:239], v159 offset:52224
	ds_read_b128 v[240:243], v159 offset:53248
	ds_read_b128 v[244:247], v159 offset:54272
	ds_read_b128 v[248:251], v159 offset:55296
	ds_read_b128 v[142:145], v159 offset:56320
	s_add_i32 m0, s98, 0x2000
	s_nop 0
	global_load_lds_dwordx4 v134, s[38:39]
	s_add_i32 m0, s98, 0x3000
	s_nop 0
	global_load_lds_dwordx4 v135, s[38:39]
	s_add_i32 m0, s98, 0x6000
	s_nop 0
	global_load_lds_dwordx4 v134, s[60:61]
	s_add_i32 m0, s98, 0x7000
	s_nop 0
	global_load_lds_dwordx4 v135, s[60:61]
	s_add_u32 s38, s38, 0x80
	s_addc_u32 s39, s39, 0
	s_add_u32 s60, s60, 0x80
	s_addc_u32 s61, s61, 0
	s_add_i32 m0, s98, 0x8000
	s_nop 0
	global_load_lds_dwordx4 v130, s[38:39]
	s_add_i32 m0, s98, 0x9000
	s_nop 0
	global_load_lds_dwordx4 v131, s[38:39]
	s_add_i32 m0, s98, 0xc000
	s_nop 0
	global_load_lds_dwordx4 v130, s[60:61]
	s_add_i32 m0, s98, 0xd000
	s_nop 0
	global_load_lds_dwordx4 v131, s[60:61]
	s_waitcnt vmcnt(8)
	s_waitcnt lgkmcnt(0)
	s_barrier
	s_setprio 1
	v_mfma_f32_16x16x32_bf16 v[126:129], v[150:153], v[188:191], v[126:129]
	v_mfma_f32_16x16x32_bf16 v[122:125], v[164:167], v[188:191], v[122:125]
	v_mfma_f32_16x16x32_bf16 v[118:121], v[150:153], v[200:203], v[118:121]
	v_mfma_f32_16x16x32_bf16 v[114:117], v[164:167], v[200:203], v[114:117]
	v_mfma_f32_16x16x32_bf16 v[102:105], v[150:153], v[208:211], v[102:105]
	v_mfma_f32_16x16x32_bf16 v[98:101], v[164:167], v[208:211], v[98:101]
	v_mfma_f32_16x16x32_bf16 v[86:89], v[150:153], v[216:219], v[86:89]
	v_mfma_f32_16x16x32_bf16 v[82:85], v[164:167], v[216:219], v[82:85]
	v_mfma_f32_16x16x32_bf16 v[126:129], v[160:163], v[196:199], v[126:129]
	v_mfma_f32_16x16x32_bf16 v[122:125], v[168:171], v[196:199], v[122:125]
	v_mfma_f32_16x16x32_bf16 v[118:121], v[160:163], v[204:207], v[118:121]
	v_mfma_f32_16x16x32_bf16 v[114:117], v[168:171], v[204:207], v[114:117]
	v_mfma_f32_16x16x32_bf16 v[102:105], v[160:163], v[212:215], v[102:105]
	v_mfma_f32_16x16x32_bf16 v[98:101], v[168:171], v[212:215], v[98:101]
	v_mfma_f32_16x16x32_bf16 v[86:89], v[160:163], v[220:223], v[86:89]
	v_mfma_f32_16x16x32_bf16 v[82:85], v[168:171], v[220:223], v[82:85]
	v_mfma_f32_16x16x32_bf16 v[110:113], v[172:175], v[188:191], v[110:113]
	v_mfma_f32_16x16x32_bf16 v[106:109], v[180:183], v[188:191], v[106:109]
	v_mfma_f32_16x16x32_bf16 v[94:97], v[172:175], v[200:203], v[94:97]
	v_mfma_f32_16x16x32_bf16 v[90:93], v[180:183], v[200:203], v[90:93]
	v_mfma_f32_16x16x32_bf16 v[78:81], v[172:175], v[208:211], v[78:81]
	v_mfma_f32_16x16x32_bf16 v[74:77], v[180:183], v[208:211], v[74:77]
	v_mfma_f32_16x16x32_bf16 v[70:73], v[172:175], v[216:219], v[70:73]
	v_mfma_f32_16x16x32_bf16 v[66:69], v[180:183], v[216:219], v[66:69]
	v_mfma_f32_16x16x32_bf16 v[110:113], v[176:179], v[196:199], v[110:113]
	v_mfma_f32_16x16x32_bf16 v[106:109], v[184:187], v[196:199], v[106:109]
	v_mfma_f32_16x16x32_bf16 v[94:97], v[176:179], v[204:207], v[94:97]
	v_mfma_f32_16x16x32_bf16 v[90:93], v[184:187], v[204:207], v[90:93]
	v_mfma_f32_16x16x32_bf16 v[78:81], v[176:179], v[212:215], v[78:81]
	v_mfma_f32_16x16x32_bf16 v[74:77], v[184:187], v[212:215], v[74:77]
	v_mfma_f32_16x16x32_bf16 v[70:73], v[176:179], v[220:223], v[70:73]
	v_mfma_f32_16x16x32_bf16 v[66:69], v[184:187], v[220:223], v[66:69]
	v_mfma_f32_16x16x32_bf16 v[62:65], v[150:153], v[224:227], v[62:65]
	v_mfma_f32_16x16x32_bf16 v[58:61], v[164:167], v[224:227], v[58:61]
	v_mfma_f32_16x16x32_bf16 v[54:57], v[150:153], v[232:235], v[54:57]
	v_mfma_f32_16x16x32_bf16 v[50:53], v[164:167], v[232:235], v[50:53]
	v_mfma_f32_16x16x32_bf16 v[38:41], v[150:153], v[240:243], v[38:41]
	v_mfma_f32_16x16x32_bf16 v[34:37], v[164:167], v[240:243], v[34:37]
	v_mfma_f32_16x16x32_bf16 v[22:25], v[150:153], v[248:251], v[22:25]
	v_mfma_f32_16x16x32_bf16 v[18:21], v[164:167], v[248:251], v[18:21]
	v_mfma_f32_16x16x32_bf16 v[62:65], v[160:163], v[228:231], v[62:65]
	v_mfma_f32_16x16x32_bf16 v[58:61], v[168:171], v[228:231], v[58:61]
	v_mfma_f32_16x16x32_bf16 v[54:57], v[160:163], v[236:239], v[54:57]
	v_mfma_f32_16x16x32_bf16 v[50:53], v[168:171], v[236:239], v[50:53]
	v_mfma_f32_16x16x32_bf16 v[38:41], v[160:163], v[244:247], v[38:41]
	v_mfma_f32_16x16x32_bf16 v[34:37], v[168:171], v[244:247], v[34:37]
	v_mfma_f32_16x16x32_bf16 v[22:25], v[160:163], v[142:145], v[22:25]
	v_mfma_f32_16x16x32_bf16 v[18:21], v[168:171], v[142:145], v[18:21]
	v_mfma_f32_16x16x32_bf16 v[46:49], v[172:175], v[224:227], v[46:49]
	v_mfma_f32_16x16x32_bf16 v[42:45], v[180:183], v[224:227], v[42:45]
	v_mfma_f32_16x16x32_bf16 v[30:33], v[172:175], v[232:235], v[30:33]
	v_mfma_f32_16x16x32_bf16 v[26:29], v[180:183], v[232:235], v[26:29]
	v_mfma_f32_16x16x32_bf16 v[14:17], v[172:175], v[240:243], v[14:17]
	v_mfma_f32_16x16x32_bf16 v[10:13], v[180:183], v[240:243], v[10:13]
	v_mfma_f32_16x16x32_bf16 v[6:9], v[172:175], v[248:251], v[6:9]
	v_mfma_f32_16x16x32_bf16 v[2:5], v[180:183], v[248:251], v[2:5]
	v_mfma_f32_16x16x32_bf16 v[46:49], v[176:179], v[228:231], v[46:49]
	v_mfma_f32_16x16x32_bf16 v[42:45], v[184:187], v[228:231], v[42:45]
	v_mfma_f32_16x16x32_bf16 v[30:33], v[176:179], v[236:239], v[30:33]
	v_mfma_f32_16x16x32_bf16 v[26:29], v[184:187], v[236:239], v[26:29]
	v_mfma_f32_16x16x32_bf16 v[14:17], v[176:179], v[244:247], v[14:17]
	v_mfma_f32_16x16x32_bf16 v[10:13], v[184:187], v[244:247], v[10:13]
	v_mfma_f32_16x16x32_bf16 v[6:9], v[176:179], v[142:145], v[6:9]
	v_mfma_f32_16x16x32_bf16 v[2:5], v[184:187], v[142:145], v[2:5]
	s_setprio 0
	s_waitcnt vmcnt(4)
	s_barrier
	s_add_i32 s58, s58, 2
	s_add_u32 s56, s56, 0x10000
	s_addc_u32 s57, s57, 0
	s_add_u32 s34, s34, 0x100
	s_addc_u32 s35, s35, 0
	s_cmp_gt_u32 s58, 61
	s_cbranch_scc0 .Lx_P1_Tloop
.Lx_P1_exit:
	s_and_b64 vcc, exec, s[16:17]
	s_cbranch_vccz .LBB0_124
	s_barrier

; __global__ void __launch_bounds__(NWAVES * 64, 2) fwd_kernel(Args args) {
;     extern __shared__ __attribute__((aligned(16))) unsigned char lds[];
	.amdhsa_kernel _Z10fwd_kernel4Args
		.amdhsa_group_segment_fixed_size 0
		.amdhsa_private_segment_fixed_size 0
		.amdhsa_kernarg_size 440
		.amdhsa_user_sgpr_count 2
		.amdhsa_user_sgpr_dispatch_ptr 0
		.amdhsa_user_sgpr_queue_ptr 0
		.amdhsa_user_sgpr_kernarg_segment_ptr 1
		.amdhsa_user_sgpr_dispatch_id 0
		.amdhsa_user_sgpr_kernarg_preload_length 0
		.amdhsa_user_sgpr_kernarg_preload_offset 0
		.amdhsa_user_sgpr_private_segment_size 0
		.amdhsa_uses_dynamic_stack 0
		.amdhsa_enable_private_segment 0
		.amdhsa_system_sgpr_workgroup_id_x 1
		.amdhsa_system_sgpr_workgroup_id_y 0
		.amdhsa_system_sgpr_workgroup_id_z 0
		.amdhsa_system_sgpr_workgroup_info 0
		.amdhsa_system_vgpr_workitem_id 0
		.amdhsa_next_free_vgpr 256
		.amdhsa_next_free_sgpr 102
		.amdhsa_accum_offset 256
		.amdhsa_reserve_vcc 1
		.amdhsa_float_round_mode_32 0
		.amdhsa_float_round_mode_16_64 0
		.amdhsa_float_denorm_mode_32 3
		.amdhsa_float_denorm_mode_16_64 3
		.amdhsa_dx10_clamp 1
		.amdhsa_ieee_mode 1
		.amdhsa_fp16_overflow 0
		.amdhsa_tg_split 0
		.amdhsa_exception_fp_ieee_invalid_op 0
		.amdhsa_exception_fp_denorm_src 0
		.amdhsa_exception_fp_ieee_div_zero 0
		.amdhsa_exception_fp_ieee_overflow 0
		.amdhsa_exception_fp_ieee_underflow 0
		.amdhsa_exception_fp_ieee_inexact 0
		.amdhsa_exception_int_div_zero 0
	.end_amdhsa_kernel

; __global__ void __launch_bounds__(NWAVES * 64, 2) fwd_kernel(Args args) {
;     extern __shared__ __attribute__((aligned(16))) unsigned char lds[];
amdhsa.kernels:
  - .agpr_count:     0
    .args:
      - .offset:         0
        .size:           184
        .value_kind:     by_value
      - .offset:         184
        .size:           4
        .value_kind:     hidden_block_count_x
      - .offset:         188
        .size:           4
        .value_kind:     hidden_block_count_y
      - .offset:         192
        .size:           4
        .value_kind:     hidden_block_count_z
      - .offset:         196
        .size:           2
        .value_kind:     hidden_group_size_x
      - .offset:         198
        .size:           2
        .value_kind:     hidden_group_size_y
      - .offset:         200
        .size:           2
        .value_kind:     hidden_group_size_z
      - .offset:         202
        .size:           2
        .value_kind:     hidden_remainder_x
      - .offset:         204
        .size:           2
        .value_kind:     hidden_remainder_y
      - .offset:         206
        .size:           2
        .value_kind:     hidden_remainder_z
      - .offset:         224
        .size:           8
        .value_kind:     hidden_global_offset_x
      - .offset:         232
        .size:           8
        .value_kind:     hidden_global_offset_y
      - .offset:         240
        .size:           8
        .value_kind:     hidden_global_offset_z
      - .offset:         248
        .size:           2
        .value_kind:     hidden_grid_dims
      - .offset:         304
        .size:           4
        .value_kind:     hidden_dynamic_lds_size
    .group_segment_fixed_size: 0
    .kernarg_segment_align: 8
    .kernarg_segment_size: 440
    .language:       OpenCL C
    .language_version:
      - 2
      - 0
    .max_flat_workgroup_size: 512
    .name:           _Z10fwd_kernel4Args
    .private_segment_fixed_size: 0
    .sgpr_count:     108
    .sgpr_spill_count: 145
    .symbol:         _Z10fwd_kernel4Args.kd
    .uniform_work_group_size: 1
    .uses_dynamic_stack: false
    .vgpr_count:     256
    .vgpr_spill_count: 0
    .wavefront_size: 64
